# down GEMM tail WGs: unit-0 arrive deferred into next unit K loop (no vmcnt0+barrier between units)
# baseline (speedup 1.0000x reference)
; #define PG8_STAGE(bufoff, gbase, voff) do { _Pragma("unroll") for (int _i = 0; _i < 2; ++_i) \
;         __builtin_amdgcn_global_load_lds((const unsigned*)((const char*)(gbase) + (voff)[_i]), (LAS unsigned*)(lds + (bufoff) + ldsw + _i * 8192), 16, 0, 0); } while (0)
; #define PG8_WAIT_V(n) asm volatile("s_waitcnt vmcnt(" #n ")" ::: "memory")
; #define PG8_BAR __builtin_amdgcn_s_barrier()
; #define PG8_ROW0(u) (tile_row0((u).pm, S.ffn) + (((u).q && (((u).q - 1) & 1)) ? HALF : 0))
; template <class Epi, bool ALIGN_EPI, bool SP2, class Ord = StaticOrder>
; __device__ __forceinline__ void gemm_phase(LAS unsigned char* lds, const Gemm g, const Ord& S, const Epi& E) {
;     ...
;     const int aoff = lds_byte(wr * 64 + fr, fq * 8), boff = lds_byte(wc * 32 + fr, fq * 8);
;     ...
;     Unit cur, nxt; int ui = 0;
;     if (!S.next(0, cur)) return;
;     f32x4 acc[2][2][4][2];
; #pragma unroll
;     for (int a = 0; a < 2; ++a)
; #pragma unroll
;         for (int b = 0; b < 2; ++b)
; #pragma unroll
;             for (int m = 0; m < 4; ++m)
; #pragma unroll
;                 for (int n = 0; n < 2; ++n) acc[a][b][m][n] = (f32x4){0.f, 0.f, 0.f, 0.f};
;     bf16x8 At[4][2], B0[2][2], B1[2][2];
;     ...
;     const char* cA = (const char*)g.A + ((size_t)PG8_ROW0(cur) * lda + (size_t)cur.pn * acs) * 2 + PG8_KOFF(cur); const char* cB = (const char*)g.Bt + (size_t)cur.pn * tstepB + PG8_KOFF(cur);
;     int ntc = PG8_NT(cur);
;     if constexpr (SP2) {
;         PG8_STAGE(PG8_SB(0, 0), cB, voffB); PG8_STAGE(PG8_SB(0, 1), cB + hstepB, voffB); PG8_STAGE(PG8_SA(0, 0), cA, voffA); PG8_STAGE(PG8_SA(0, 1), cA + hstepA, voffA);
;         if (wr == 1) PG8_BAR;
;         PG8_WAIT_V(2); PG8_BAR;
;         PG8_STAGE(PG8_SB(1, 0), cB + kstep, voffB); PG8_STAGE(PG8_SA(1, 0), cA + kstep, voffA); PG8_STAGE(PG8_SB(1, 1), cB + hstepB + kstep, voffB);
;         PG8_WAIT_V(6); PG8_BAR;
;     } else {
;         PG8_STAGE(PG8_SB(0, 0), cB, voffB); PG8_STAGE(PG8_SA(0, 0), cA, voffA); PG8_STAGE(PG8_SB(0, 1), cB + hstepB, voffB); PG8_STAGE(PG8_SA(0, 1), cA + hstepA, voffA);
;         if (wr == 1) PG8_BAR;
;         PG8_WAIT_V(4); PG8_BAR;
;         PG8_STAGE(PG8_SB(1, 0), cB + kstep, voffB); PG8_STAGE(PG8_SA(1, 0), cA + kstep, voffA); PG8_STAGE(PG8_SB(1, 1), cB + hstepB + kstep, voffB);
;         PG8_WAIT_V(6); PG8_BAR;
;     }
.LBB0_1436:
	s_and_b64 s[4:5], s[4:5], exec
	v_readlane_b32 s4, v239, 0
	v_readlane_b32 s5, v239, 1
	s_cselect_b32 s54, s18, s27
	s_and_b64 s[4:5], s[4:5], exec
	v_readlane_b32 s4, v244, 58
	v_readlane_b32 s5, v244, 59
	s_mov_b32 s7, s5
	v_writelane_b32 v244, s4, 58
	s_cselect_b32 s25, s37, 0
	s_cselect_b32 s24, s36, 0
	s_lshl_b32 s6, s53, 8
	v_writelane_b32 v244, s5, 59
	s_lshl_b64 s[4:5], s[6:7], 2
	v_readlane_b32 s6, v244, 16
	s_add_u32 s53, s6, s4
	v_readlane_b32 s4, v244, 17
	s_addc_u32 s56, s4, s5
	s_add_i32 m0, s19, 0x18000
	v_lshl_add_u64 v[2:3], v[2:3], 0, s[30:31]
	s_waitcnt vmcnt(2)
	s_barrier
	global_load_lds_dwordx4 v[2:3], off
	v_lshl_add_u64 v[2:3], v[4:5], 0, s[30:31]
	s_add_i32 m0, s19, 0x1a000
	s_add_i32 s57, s19, 0x8000
	global_load_lds_dwordx4 v[2:3], off
	v_lshl_add_u64 v[2:3], v[10:11], 0, s[30:31]
	s_mov_b32 m0, s57
	s_add_i32 s58, s19, 0xa000
	global_load_lds_dwordx4 v[2:3], off
	v_lshl_add_u64 v[2:3], v[12:13], 0, s[30:31]
	s_mov_b32 m0, s58
	v_bfe_u32 v23, v18, 4, 2
	global_load_lds_dwordx4 v[2:3], off
	s_add_i32 m0, s19, 0x1c000
	v_lshl_add_u64 v[2:3], v[6:7], 0, s[30:31]
	global_load_lds_dwordx4 v[2:3], off
	v_lshl_add_u64 v[2:3], v[8:9], 0, s[30:31]
	s_add_i32 m0, s19, 0x1e000
	v_and_b32_e32 v22, 15, v18
	global_load_lds_dwordx4 v[2:3], off
	v_lshlrev_b32_e32 v25, 4, v23
	v_lshlrev_b32_e32 v18, 2, v18
	s_and_b32 s4, s9, 3
	v_lshl_or_b32 v26, v22, 6, v25
	s_lshl_b32 s5, s10, 13
	v_and_b32_e32 v18, 32, v18
	v_bitop3_b32 v27, v26, s5, v18 bitop3:0xde
	s_lshl_b32 s5, s4, 12
	v_lshlrev_b32_e32 v24, 3, v23
	s_cmpk_lt_u32 s8, 0x100
	v_bitop3_b32 v232, v26, s5, v18 bitop3:0xde
	v_lshl_or_b32 v233, s4, 5, v24
	s_cselect_b64 s[34:35], -1, 0
	s_and_b32 s5, s8, 0x3fffff00
	s_lshl_b32 s4, s4, 6
	s_or_b32 s4, s4, s5
	v_or3_b32 v2, s4, v25, v22
	v_lshlrev_b32_e32 v2, 2, v2
	v_readlane_b32 s8, v245, 47
	v_ashrrev_i32_e32 v3, 31, v2
	v_readlane_b32 s9, v245, 48
	s_waitcnt vmcnt(6)
	v_or_b32_e32 v4, v23, v22
	s_cmp_lg_u64 s[24:25], 0
	v_lshl_add_u64 v[210:211], v[2:3], 2, s[8:9]
	v_add_u32_e32 v2, v16, v14
	v_add_lshl_u32 v18, v2, v15, 1
	v_add_u32_e32 v2, v21, v17
	v_lshl_add_u64 v[212:213], s[12:13], 0, v[18:19]
	v_add_lshl_u32 v18, v2, v20, 1
	s_mov_b32 s52, 0
	s_mov_b32 s101, 0
	v_lshl_or_b32 v231, s10, 6, v22
	v_cmp_eq_u32_e64 s[4:5], 0, v4
	v_cmp_eq_u32_e64 s[6:7], 0, v23
	s_cselect_b64 s[38:39], -1, 0
	v_lshl_add_u64 v[214:215], s[12:13], 0, v[18:19]
	v_add_u32_e32 v234, 0, v27
	s_barrier
	s_branch .LBB0_1439

;     __device__ __forceinline__ void operator()(f32x4 (&acc)[2][2][4][2], const Unit& u, int row0t, int wr, int wc, int fr, int fq) const {
;     ...
;                 asm volatile("s_waitcnt vmcnt(0)" ::: "memory");
;                 if (fr == 0 && fq == 0) __hip_atomic_fetch_add(flag + pi, 1u, __ATOMIC_RELAXED, __HIP_MEMORY_SCOPE_AGENT);
.La1d_do:
	v_cmp_eq_u32_e64 s[98:99], 0, v0
	s_nop 3
	s_mov_b64 exec, s[98:99]
	s_cbranch_execz .La1d_x
	v_readlane_b32 s98, v245, 33
	v_readlane_b32 s99, v245, 34
	v_mov_b32_e32 v247, 0
	v_mov_b32_e32 v248, 1
	s_nop 3
	s_add_u32 s98, s98, s101
	s_addc_u32 s99, s99, 0
	global_atomic_add v247, v248, s[98:99]
.La1d_x:
	s_mov_b64 exec, -1
	s_mov_b32 s101, 0
	s_branch .La1d_back

; #define PG8_STAGE(bufoff, gbase, voff) do { _Pragma("unroll") for (int _i = 0; _i < 2; ++_i) \
;         __builtin_amdgcn_global_load_lds((const unsigned*)((const char*)(gbase) + (voff)[_i]), (LAS unsigned*)(lds + (bufoff) + ldsw + _i * 8192), 16, 0, 0); } while (0)
; #define PG8_LDA(dst, b, h) do { _Pragma("unroll") for (int m = 0; m < 4; ++m) _Pragma("unroll") for (int k = 0; k < 2; ++k) dst[m][k] = *(const LAS bf16x8*)(lds + PG8_SA(b, h) + aoff + m * 2048 + k * 1024); } while (0)
; #define PG8_LDB(dst, b, h) do { _Pragma("unroll") for (int n = 0; n < 2; ++n) _Pragma("unroll") for (int k = 0; k < 2; ++k) dst[n][k] = *(const LAS bf16x8*)(lds + PG8_SB(b, h) + boff + n * 2048 + k * 1024); } while (0)
; #define PG8_WAIT_V(n) asm volatile("s_waitcnt vmcnt(" #n ")" ::: "memory")
; #define PG8_WAIT_L(n) asm volatile("s_waitcnt lgkmcnt(" #n ")" ::: "memory")
; #define PG8_BAR __builtin_amdgcn_s_barrier()
; #define PG8_SCHED __builtin_amdgcn_sched_barrier(0)
; template <class Epi, bool ALIGN_EPI, bool SP2, class Ord = StaticOrder>
; __device__ __forceinline__ void gemm_phase(LAS unsigned char* lds, const Gemm g, const Ord& S, const Epi& E) {
;     ...
;             PG8_WAIT_V(8); PG8_WAIT_L(0); PG8_BAR; PG8_MMA(0, 0, At, B0); PG8_MMA(0, 1, At, B1); PG8_BAR; PG8_SCHED;
;             PG8_LDA(At, 0, 1); PG8_STAGE(PG8_SB(0, 0), b2, voffB); PG8_STAGE(PG8_SB(0, 1), b2 + hstepB, voffB); PG8_STAGE(PG8_SA(0, 0), a2, voffA);
;             PG8_WAIT_V(8); PG8_WAIT_L(0); PG8_BAR; if (full) { PG8_MMA(1, 0, At, B0); PG8_MMA(1, 1, At, B1); } PG8_BAR; PG8_SCHED;
;             PG8_LDB(B0, 1, 0); PG8_LDB(B1, 1, 1); PG8_SCHED; PG8_LDA(At, 1, 0); PG8_STAGE(PG8_SA(0, 1), a2 + hstepA, voffA);
;             PG8_WAIT_V(8); PG8_WAIT_L(0); PG8_BAR; PG8_MMA(0, 0, At, B0); PG8_MMA(0, 1, At, B1); PG8_BAR; PG8_SCHED;
;             PG8_LDA(At, 1, 1); PG8_STAGE(PG8_SB(1, 0), b3, voffB); PG8_STAGE(PG8_SB(1, 1), b3 + hstepB, voffB); PG8_STAGE(PG8_SA(1, 0), a3, voffA);
;             PG8_WAIT_V(8); PG8_WAIT_L(0); PG8_BAR; if (full) { PG8_MMA(1, 0, At, B0); PG8_MMA(1, 1, At, B1); } PG8_BAR; PG8_SCHED;
;     __device__ __forceinline__ void operator()(f32x4 (&acc)[2][2][4][2], const Unit& u, int row0t, int wr, int wc, int fr, int fq) const {
;     ...
;                 if (fr == 0 && fq == 0) __hip_atomic_fetch_add(flag + pi, 1u, __ATOMIC_RELAXED, __HIP_MEMORY_SCOPE_AGENT);
.LBB0_1449:
	s_barrier
	s_cmp_lg_u32 s101, 0
	s_cbranch_scc1 .La1d_do
; #define PG8_STAGE(bufoff, gbase, voff) do { _Pragma("unroll") for (int _i = 0; _i < 2; ++_i) \
;         __builtin_amdgcn_global_load_lds((const unsigned*)((const char*)(gbase) + (voff)[_i]), (LAS unsigned*)(lds + (bufoff) + ldsw + _i * 8192), 16, 0, 0); } while (0)
; #define PG8_LDA(dst, b, h) do { _Pragma("unroll") for (int m = 0; m < 4; ++m) _Pragma("unroll") for (int k = 0; k < 2; ++k) dst[m][k] = *(const LAS bf16x8*)(lds + PG8_SA(b, h) + aoff + m * 2048 + k * 1024); } while (0)
; #define PG8_LDB(dst, b, h) do { _Pragma("unroll") for (int n = 0; n < 2; ++n) _Pragma("unroll") for (int k = 0; k < 2; ++k) dst[n][k] = *(const LAS bf16x8*)(lds + PG8_SB(b, h) + boff + n * 2048 + k * 1024); } while (0)
; #define PG8_MMA(ai, bj, At, Bt) do { __builtin_amdgcn_s_setprio(1); _Pragma("unroll") for (int m = 0; m < 4; ++m) _Pragma("unroll") for (int n = 0; n < 2; ++n) _Pragma("unroll") for (int k = 0; k < 2; ++k) \
;         acc[ai][bj][m][n] = __builtin_amdgcn_mfma_f32_16x16x32_bf16(Bt[n][k], At[m][k], acc[ai][bj][m][n], 0, 0, 0); __builtin_amdgcn_s_setprio(0); } while (0)
; #define PG8_WAIT_V(n) asm volatile("s_waitcnt vmcnt(" #n ")" ::: "memory")
; #define PG8_WAIT_L(n) asm volatile("s_waitcnt lgkmcnt(" #n ")" ::: "memory")
; #define PG8_BAR __builtin_amdgcn_s_barrier()
; #define PG8_SCHED __builtin_amdgcn_sched_barrier(0)
; template <class Epi, bool ALIGN_EPI, bool SP2, class Ord = StaticOrder>
; __device__ __forceinline__ void gemm_phase(LAS unsigned char* lds, const Gemm g, const Ord& S, const Epi& E) {
;     ...
;         for (int t = 0; t < ntc; t += 2) {
;     ...
;             PG8_LDB(B0, 1, 0); PG8_LDB(B1, 1, 1); PG8_SCHED; PG8_LDA(At, 1, 0); PG8_STAGE(PG8_SA(0, 1), a2 + hstepA, voffA);
;             PG8_WAIT_V(8); PG8_WAIT_L(0); PG8_BAR; PG8_MMA(0, 0, At, B0); PG8_MMA(0, 1, At, B1); PG8_BAR; PG8_SCHED;
;             PG8_LDA(At, 1, 1); PG8_STAGE(PG8_SB(1, 0), b3, voffB); PG8_STAGE(PG8_SB(1, 1), b3 + hstepB, voffB); PG8_STAGE(PG8_SA(1, 0), a3, voffA);
;             PG8_WAIT_V(8); PG8_WAIT_L(0); PG8_BAR; if (full) { PG8_MMA(1, 0, At, B0); PG8_MMA(1, 1, At, B1); } PG8_BAR; PG8_SCHED;
.La1d_back:
	s_add_i32 s68, 0, 0x18000
	v_add_u32_e32 v18, s68, v232
	s_add_i32 s69, 0, 0x1c000
	ds_read_b128 v[150:153], v18
	ds_read_b128 v[154:157], v18 offset:1024
	ds_read_b128 v[158:161], v18 offset:2048
	ds_read_b128 v[162:165], v18 offset:3072
	v_add_u32_e32 v18, s69, v232
	ds_read_b128 v[134:137], v18
	ds_read_b128 v[138:141], v18 offset:1024
	ds_read_b128 v[142:145], v18 offset:2048
	ds_read_b128 v[146:149], v18 offset:3072
	s_add_u32 s48, s48, s12
	s_addc_u32 s49, s49, s13
	s_mov_b32 m0, s29
	v_lshl_add_u64 v[236:237], s[48:49], 0, v[202:203]
	s_waitcnt lgkmcnt(0)
	ds_read_b128 v[166:169], v234 offset:32768
	ds_read_b128 v[170:173], v234 offset:33792
	ds_read_b128 v[174:177], v234 offset:34816
	ds_read_b128 v[178:181], v234 offset:35840
	ds_read_b128 v[182:185], v234 offset:36864
	ds_read_b128 v[186:189], v234 offset:37888
	ds_read_b128 v[190:193], v234 offset:38912
	ds_read_b128 v[194:197], v234 offset:39936
	global_load_lds_dwordx4 v[236:237], off
	v_lshl_add_u64 v[236:237], s[48:49], 0, v[206:207]
	s_mov_b32 m0, s33
	s_nop 0
	global_load_lds_dwordx4 v[236:237], off
	s_waitcnt vmcnt(8)
	s_waitcnt lgkmcnt(0)
	s_barrier
	s_setprio 1
	s_waitcnt lgkmcnt(0)
	v_mfma_f32_16x16x32_bf16 v[126:129], v[150:153], v[166:169], v[126:129]
	v_mfma_f32_16x16x32_bf16 v[130:133], v[158:161], v[166:169], v[130:133]
	v_mfma_f32_16x16x32_bf16 v[114:117], v[150:153], v[174:177], v[114:117]
	v_mfma_f32_16x16x32_bf16 v[110:113], v[158:161], v[174:177], v[110:113]
	v_mfma_f32_16x16x32_bf16 v[98:101], v[150:153], v[182:185], v[98:101]
	v_mfma_f32_16x16x32_bf16 v[94:97], v[158:161], v[182:185], v[94:97]
	v_mfma_f32_16x16x32_bf16 v[82:85], v[150:153], v[190:193], v[82:85]
	v_mfma_f32_16x16x32_bf16 v[78:81], v[158:161], v[190:193], v[78:81]
	v_mfma_f32_16x16x32_bf16 v[126:129], v[154:157], v[170:173], v[126:129]
	v_mfma_f32_16x16x32_bf16 v[130:133], v[162:165], v[170:173], v[130:133]
	v_mfma_f32_16x16x32_bf16 v[114:117], v[154:157], v[178:181], v[114:117]
	v_mfma_f32_16x16x32_bf16 v[110:113], v[162:165], v[178:181], v[110:113]
	v_mfma_f32_16x16x32_bf16 v[98:101], v[154:157], v[186:189], v[98:101]
	v_mfma_f32_16x16x32_bf16 v[94:97], v[162:165], v[186:189], v[94:97]
	v_mfma_f32_16x16x32_bf16 v[82:85], v[154:157], v[194:197], v[82:85]
	v_mfma_f32_16x16x32_bf16 v[78:81], v[162:165], v[194:197], v[78:81]
	s_setprio 0
	s_setprio 1
	v_mfma_f32_16x16x32_bf16 v[122:125], v[134:137], v[166:169], v[122:125]
	v_mfma_f32_16x16x32_bf16 v[118:121], v[142:145], v[166:169], v[118:121]
	v_mfma_f32_16x16x32_bf16 v[106:109], v[134:137], v[174:177], v[106:109]
	v_mfma_f32_16x16x32_bf16 v[102:105], v[142:145], v[174:177], v[102:105]
	v_mfma_f32_16x16x32_bf16 v[90:93], v[134:137], v[182:185], v[90:93]
	v_mfma_f32_16x16x32_bf16 v[86:89], v[142:145], v[182:185], v[86:89]
	v_mfma_f32_16x16x32_bf16 v[74:77], v[134:137], v[190:193], v[74:77]
	v_mfma_f32_16x16x32_bf16 v[70:73], v[142:145], v[190:193], v[70:73]
	v_mfma_f32_16x16x32_bf16 v[122:125], v[138:141], v[170:173], v[122:125]
	v_mfma_f32_16x16x32_bf16 v[118:121], v[146:149], v[170:173], v[118:121]
	v_mfma_f32_16x16x32_bf16 v[106:109], v[138:141], v[178:181], v[106:109]
	v_mfma_f32_16x16x32_bf16 v[102:105], v[146:149], v[178:181], v[102:105]
	v_mfma_f32_16x16x32_bf16 v[90:93], v[138:141], v[186:189], v[90:93]
	v_mfma_f32_16x16x32_bf16 v[86:89], v[146:149], v[186:189], v[86:89]
	v_mfma_f32_16x16x32_bf16 v[74:77], v[138:141], v[194:197], v[74:77]
	v_mfma_f32_16x16x32_bf16 v[70:73], v[146:149], v[194:197], v[70:73]
	s_setprio 0
	s_barrier
	s_add_i32 s48, s68, s1
	v_lshl_add_u64 v[20:21], v[20:21], 0, s[30:31]
	s_mov_b32 m0, s48
	ds_read_b128 v[190:193], v234 offset:49152
	ds_read_b128 v[194:197], v234 offset:50176
	ds_read_b128 v[182:185], v234 offset:51200
	ds_read_b128 v[186:189], v234 offset:52224
	ds_read_b128 v[174:177], v234 offset:53248
	ds_read_b128 v[178:181], v234 offset:54272
	ds_read_b128 v[166:169], v234 offset:55296
	ds_read_b128 v[170:173], v234 offset:56320
	global_load_lds_dwordx4 v[20:21], off
	v_lshl_add_u64 v[20:21], v[216:217], 0, s[30:31]
	s_add_i32 m0, s48, 0x2000
	s_add_i32 s48, s69, s1
	global_load_lds_dwordx4 v[20:21], off
	v_lshl_add_u64 v[20:21], v[218:219], 0, s[30:31]
	s_mov_b32 m0, s48
	s_andn2_b64 vcc, exec, s[50:51]
	global_load_lds_dwordx4 v[20:21], off
	v_lshl_add_u64 v[20:21], v[220:221], 0, s[30:31]
	s_add_i32 m0, s48, 0x2000
	s_nop 0
	global_load_lds_dwordx4 v[20:21], off
	v_lshl_add_u64 v[20:21], v[222:223], 0, s[30:31]
	s_mov_b32 m0, s57
	s_nop 0
	global_load_lds_dwordx4 v[20:21], off
	v_lshl_add_u64 v[20:21], v[224:225], 0, s[30:31]
	s_mov_b32 m0, s58
	s_nop 0
	global_load_lds_dwordx4 v[20:21], off
	s_waitcnt vmcnt(8)
	s_waitcnt lgkmcnt(0)
	s_barrier
	s_cbranch_vccnz .LBB0_1446
	s_setprio 1
	s_waitcnt lgkmcnt(0)
	v_mfma_f32_16x16x32_bf16 v[62:65], v[150:153], v[190:193], v[62:65]
	v_mfma_f32_16x16x32_bf16 v[66:69], v[158:161], v[190:193], v[66:69]
	v_mfma_f32_16x16x32_bf16 v[46:49], v[150:153], v[182:185], v[46:49]
	v_mfma_f32_16x16x32_bf16 v[50:53], v[158:161], v[182:185], v[50:53]
	v_mfma_f32_16x16x32_bf16 v[30:33], v[150:153], v[174:177], v[30:33]
	v_mfma_f32_16x16x32_bf16 v[34:37], v[158:161], v[174:177], v[34:37]
	v_mfma_f32_16x16x32_bf16 v[10:13], v[150:153], v[166:169], v[10:13]
	v_mfma_f32_16x16x32_bf16 v[14:17], v[158:161], v[166:169], v[14:17]
	v_mfma_f32_16x16x32_bf16 v[62:65], v[154:157], v[194:197], v[62:65]
	v_mfma_f32_16x16x32_bf16 v[66:69], v[162:165], v[194:197], v[66:69]
	v_mfma_f32_16x16x32_bf16 v[46:49], v[154:157], v[186:189], v[46:49]
	v_mfma_f32_16x16x32_bf16 v[50:53], v[162:165], v[186:189], v[50:53]
	v_mfma_f32_16x16x32_bf16 v[30:33], v[154:157], v[178:181], v[30:33]
	v_mfma_f32_16x16x32_bf16 v[34:37], v[162:165], v[178:181], v[34:37]
	v_mfma_f32_16x16x32_bf16 v[10:13], v[154:157], v[170:173], v[10:13]
	v_mfma_f32_16x16x32_bf16 v[14:17], v[162:165], v[170:173], v[14:17]
	s_setprio 0
	s_setprio 1
	v_mfma_f32_16x16x32_bf16 v[54:57], v[134:137], v[190:193], v[54:57]
	v_mfma_f32_16x16x32_bf16 v[58:61], v[142:145], v[190:193], v[58:61]
	v_mfma_f32_16x16x32_bf16 v[38:41], v[134:137], v[182:185], v[38:41]
	v_mfma_f32_16x16x32_bf16 v[42:45], v[142:145], v[182:185], v[42:45]
	v_mfma_f32_16x16x32_bf16 v[20:23], v[134:137], v[174:177], v[22:25]
	v_mfma_f32_16x16x32_bf16 v[26:29], v[142:145], v[174:177], v[26:29]
	v_mfma_f32_16x16x32_bf16 v[2:5], v[134:137], v[166:169], v[2:5]
	v_mfma_f32_16x16x32_bf16 v[6:9], v[142:145], v[166:169], v[6:9]
	v_mfma_f32_16x16x32_bf16 v[54:57], v[138:141], v[194:197], v[54:57]
	v_mfma_f32_16x16x32_bf16 v[58:61], v[146:149], v[194:197], v[58:61]
	v_mfma_f32_16x16x32_bf16 v[38:41], v[138:141], v[186:189], v[38:41]
	v_mfma_f32_16x16x32_bf16 v[42:45], v[146:149], v[186:189], v[42:45]
	v_mfma_f32_16x16x32_bf16 v[22:25], v[138:141], v[178:181], v[20:23]
	v_mfma_f32_16x16x32_bf16 v[26:29], v[146:149], v[178:181], v[26:29]
	v_mfma_f32_16x16x32_bf16 v[2:5], v[138:141], v[170:173], v[2:5]
	v_mfma_f32_16x16x32_bf16 v[6:9], v[146:149], v[170:173], v[6:9]
	s_setprio 0
	s_branch .LBB0_1446

; #define PG8_BAR __builtin_amdgcn_s_barrier()
; template <class Epi, bool ALIGN_EPI, bool SP2, class Ord = StaticOrder>
; __device__ __forceinline__ void gemm_phase(LAS unsigned char* lds, const Gemm g, const Ord& S, const Epi& E) {
;     ...
;         cur = nxt; cA = nA; cB = nB; ntc = PG8_NT(cur); ++ui;
;         if constexpr (ALIGN_EPI) { if (wr == 1) PG8_BAR; }
;     __device__ __forceinline__ void operator()(f32x4 (&acc)[2][2][4][2], const Unit& u, int row0t, int wr, int wc, int fr, int fq) const {
;     ...
;                         for (int n = 0; n < 2; ++n) asm volatile("global_store_dwordx4 %0, %1, off sc0 sc1" :: "v"(pp + ((m * 2 + bj) * 2 + n) * 2048), "v"(acc[0][bj][m][n]) : "memory");
;                 asm volatile("s_waitcnt vmcnt(0)" ::: "memory");
;                 if (fr == 0 && fq == 0) __hip_atomic_fetch_add(flag + pi, 1u, __ATOMIC_RELAXED, __HIP_MEMORY_SCOPE_AGENT);
.LBB0_1487:
	v_readlane_b32 s98, v239, 0
	s_nop 3
	s_cmp_lg_u32 s98, 0
	s_cselect_b32 s101, 0x100, 0
	s_add_i32 s101, s101, 0xc000
	s_cmp_eq_u32 s61, 0
	s_cselect_b32 s54, s27, s18
	s_andn2_b64 vcc, exec, s[22:23]
	s_cbranch_vccnz .LBB0_1437
	s_barrier
	s_branch .LBB0_1437
